# v23 + attention-merge loop two iterations per trip (14 loads in flight)
# baseline (speedup 1.0000x reference)
; #define MRG(F) o.F = pk_bf16((w0 * bflo(a.F) + w1 * bflo(bq.F) + w2 * bflo(cq.F)) * bflo(gq.F), (w0 * bfhi(a.F) + w1 * bfhi(bq.F) + w2 * bfhi(cq.F)) * bfhi(gq.F))
; __device__ __forceinline__ void merge_phase(u16* OG, const float* LSE, const u16* AG, int bid, int nb) {
;     for (int idx = bid * 512 + threadIdx.x; idx < TT * 64; idx += nb * 512) {
;         const int tok = idx >> 6, h = (idx >> 3) & 7, ch = idx & 7; const size_t off = (size_t)tok * 512 + h * 64 + 8 * ch;
;         const float l0 = LSE[(size_t)tok * 8 + h], l1 = LSE[(size_t)TT * 8 + (size_t)tok * 8 + h], l2 = LSE[(size_t)2 * TT * 8 + (size_t)tok * 8 + h];
;         const float m = fmaxf(l0, fmaxf(l1, l2)); float w0 = __builtin_amdgcn_exp2f(l0 - m), w1 = __builtin_amdgcn_exp2f(l1 - m), w2 = __builtin_amdgcn_exp2f(l2 - m);
;         const float inv = 1.0f / (w0 + w1 + w2); w0 *= inv; w1 *= inv; w2 *= inv;
;         const u32x4 a = *(const u32x4*)(OG + off), bq = *(const u32x4*)(OG + (size_t)TT * 512 + off), cq = *(const u32x4*)(OG + (size_t)2 * TT * 512 + off), gq = *(const u32x4*)(AG + off);
;         u32x4 o;
;     ...
;         MRG(x); MRG(y); MRG(z); MRG(w);
.Ls3d_skip:
	s_mov_b64 exec, s[6:7]
	s_barrier
	s_add_u32 s4, s76, 0x1000000
	s_addc_u32 s5, s77, 0
	s_lshl_b32 s6, s2, 9
	v_add_u32_e32 v1, s6, v188
	v_add_u32_e32 v0, 0xffff8000, v1
	s_mov_b32 s16, 0x100000
	v_cmp_gt_i32_e32 vcc, s16, v0
	s_and_saveexec_b64 s[6:7], vcc
	s_cbranch_execz .LBB0_450
	s_add_u32 s8, s78, 0x1b00000
	s_addc_u32 s9, s79, 0
	s_add_u32 s10, s76, 0x3000000
	s_addc_u32 s11, s77, 0
	s_add_u32 s12, s76, 0x2000000
	s_addc_u32 s13, s77, 0
	v_add_u32_e32 v2, 0xfffe0000, v1
	v_lshlrev_b32_e32 v3, 3, v0
	s_mov_b64 s[14:15], 0
	v_mov_b32_e32 v1, 0
	s_mov_b32 s17, 0x80000
	s_mov_b32 s18, 0xe7fff
	v_mov_b32_e32 v49, 0
.Lmg_top:
	v_readfirstlane_b32 s22, v2
	s_nop 3
	s_add_i32 s24, s22, 0x30000
	s_cmp_gt_i32 s24, 0xfffff
	s_cbranch_scc1 .Lmg_tail
	v_add_u32_e32 v2, 0x18000, v2
	v_ashrrev_i32_e32 v4, 6, v2
	v_ashrrev_i32_e32 v5, 31, v4
	v_bfe_u32 v0, v2, 3, 3
	v_lshlrev_b64 v[6:7], 9, v[4:5]
	v_lshlrev_b64 v[4:5], 5, v[4:5]
	v_lshlrev_b32_e32 v9, 6, v0
	v_lshlrev_b32_e32 v0, 2, v0
	v_lshl_add_u64 v[4:5], s[8:9], 0, v[4:5]
	v_lshl_add_u64 v[20:21], v[4:5], 0, v[0:1]
	v_and_b32_e32 v8, 56, v3
	v_add_co_u32_e32 v22, vcc, s17, v20
	v_or3_b32 v6, v6, v9, v8
	s_nop 0
	v_addc_co_u32_e32 v23, vcc, 0, v21, vcc
	v_lshlrev_b64 v[4:5], 1, v[6:7]
	v_add_co_u32_e32 v24, vcc, s16, v20
	v_lshl_add_u64 v[26:27], s[76:77], 0, v[4:5]
	s_nop 0
	v_addc_co_u32_e32 v25, vcc, 0, v21, vcc
	v_lshl_add_u64 v[28:29], s[4:5], 0, v[4:5]
	v_lshl_add_u64 v[30:31], s[12:13], 0, v[4:5]
	v_lshl_add_u64 v[32:33], s[10:11], 0, v[4:5]
	global_load_dword v0, v[20:21], off
	global_load_dword v40, v[22:23], off
	global_load_dword v41, v[24:25], off
	global_load_dwordx4 v[4:7], v[28:29], off
	global_load_dwordx4 v[8:11], v[26:27], off
	global_load_dwordx4 v[12:15], v[30:31], off
	global_load_dwordx4 v[16:19], v[32:33], off
	v_add_u32_e32 v3, 0xc0000, v3
	v_add_u32_e32 v2, 0x18000, v2
	v_ashrrev_i32_e32 v52, 6, v2
	v_ashrrev_i32_e32 v53, 31, v52
	v_bfe_u32 v48, v2, 3, 3
	v_lshlrev_b64 v[54:55], 9, v[52:53]
	v_lshlrev_b64 v[52:53], 5, v[52:53]
	v_lshlrev_b32_e32 v57, 6, v48
	v_lshlrev_b32_e32 v48, 2, v48
	v_lshl_add_u64 v[52:53], s[8:9], 0, v[52:53]
	v_lshl_add_u64 v[68:69], v[52:53], 0, v[48:49]
	v_and_b32_e32 v56, 56, v3
	v_add_co_u32_e32 v70, vcc, s17, v68
	v_or3_b32 v54, v54, v57, v56
	s_nop 0
	v_addc_co_u32_e32 v71, vcc, 0, v69, vcc
	v_lshlrev_b64 v[52:53], 1, v[54:55]
	v_add_co_u32_e32 v72, vcc, s16, v68
	v_lshl_add_u64 v[74:75], s[76:77], 0, v[52:53]
	s_nop 0
	v_addc_co_u32_e32 v73, vcc, 0, v69, vcc
	v_lshl_add_u64 v[76:77], s[4:5], 0, v[52:53]
	v_lshl_add_u64 v[78:79], s[12:13], 0, v[52:53]
	v_lshl_add_u64 v[80:81], s[10:11], 0, v[52:53]
	global_load_dword v48, v[68:69], off
	global_load_dword v88, v[70:71], off
	global_load_dword v89, v[72:73], off
	global_load_dwordx4 v[52:55], v[76:77], off
	global_load_dwordx4 v[56:59], v[74:75], off
	global_load_dwordx4 v[60:63], v[78:79], off
	global_load_dwordx4 v[64:67], v[80:81], off
	v_add_u32_e32 v3, 0xc0000, v3
	s_waitcnt vmcnt(11)
	v_max3_f32 v42, v0, v40, v41
	v_sub_f32_e32 v0, v0, v42
	s_waitcnt vmcnt(10)
	v_lshlrev_b32_e32 v20, 16, v4
	s_waitcnt vmcnt(9)
	v_and_b32_e32 v21, 0xffff0000, v8
	s_waitcnt vmcnt(7)
; __device__ __forceinline__ void store16_wt(void* p, u32x4 v) { asm volatile("global_store_dwordx4 %0, %1, off sc1\n\ts_nop 1" :: "v"(p), "v"(v) : "memory"); }
; #define MRG(F) o.F = pk_bf16((w0 * bflo(a.F) + w1 * bflo(bq.F) + w2 * bflo(cq.F)) * bflo(gq.F), (w0 * bfhi(a.F) + w1 * bfhi(bq.F) + w2 * bfhi(cq.F)) * bfhi(gq.F))
; __device__ __forceinline__ void merge_phase(u16* OG, const float* LSE, const u16* AG, int bid, int nb) {
;     ...
;         const int tok = idx >> 6, h = (idx >> 3) & 7, ch = idx & 7; const size_t off = (size_t)tok * 512 + h * 64 + 8 * ch;
;         const float l0 = LSE[(size_t)tok * 8 + h], l1 = LSE[(size_t)TT * 8 + (size_t)tok * 8 + h], l2 = LSE[(size_t)2 * TT * 8 + (size_t)tok * 8 + h];
;         const float m = fmaxf(l0, fmaxf(l1, l2)); float w0 = __builtin_amdgcn_exp2f(l0 - m), w1 = __builtin_amdgcn_exp2f(l1 - m), w2 = __builtin_amdgcn_exp2f(l2 - m);
;         const float inv = 1.0f / (w0 + w1 + w2); w0 *= inv; w1 *= inv; w2 *= inv;
;         const u32x4 a = *(const u32x4*)(OG + off), bq = *(const u32x4*)(OG + (size_t)TT * 512 + off), cq = *(const u32x4*)(OG + (size_t)2 * TT * 512 + off), gq = *(const u32x4*)(AG + off);
;         u32x4 o;
;     ...
;         MRG(x); MRG(y); MRG(z); MRG(w);
;     ...
;         store16_wt(OG + off, o);
;     }
	v_lshlrev_b32_e32 v36, 16, v18
	v_and_b32_e32 v37, 0xffff0000, v18
	v_sub_f32_e32 v18, v40, v42
	v_lshlrev_b32_e32 v22, 16, v8
	v_and_b32_e32 v23, 0xffff0000, v4
	v_lshlrev_b32_e32 v24, 16, v12
	v_and_b32_e32 v25, 0xffff0000, v12
	v_lshlrev_b32_e32 v28, 16, v16
	v_and_b32_e32 v29, 0xffff0000, v16
	v_and_b32_e32 v31, 0xffff0000, v9
	v_lshlrev_b32_e32 v4, 16, v9
	v_lshlrev_b32_e32 v8, 16, v13
	v_and_b32_e32 v9, 0xffff0000, v13
	v_lshlrev_b32_e32 v12, 16, v17
	v_and_b32_e32 v13, 0xffff0000, v17
	v_lshlrev_b32_e32 v16, 16, v6
	v_and_b32_e32 v17, 0xffff0000, v10
	v_lshlrev_b32_e32 v32, 16, v10
	v_and_b32_e32 v33, 0xffff0000, v6
	v_lshlrev_b32_e32 v34, 16, v14
	v_and_b32_e32 v35, 0xffff0000, v14
	v_and_b32_e32 v39, 0xffff0000, v11
	v_lshlrev_b32_e32 v6, 16, v11
	v_lshlrev_b32_e32 v10, 16, v15
	v_and_b32_e32 v11, 0xffff0000, v15
	v_lshlrev_b32_e32 v14, 16, v19
	v_and_b32_e32 v15, 0xffff0000, v19
	v_sub_f32_e32 v40, v41, v42
	v_exp_f32_e32 v19, v0
	v_exp_f32_e32 v18, v18
	v_exp_f32_e32 v40, v40
	v_lshlrev_b32_e32 v30, 16, v5
	v_and_b32_e32 v5, 0xffff0000, v5
	v_add_f32_e32 v0, v19, v18
	v_add_f32_e32 v0, v40, v0
	v_div_scale_f32 v41, s[20:21], v0, v0, 1.0
	v_rcp_f32_e32 v43, v41
	v_div_scale_f32 v42, vcc, 1.0, v0, 1.0
	v_lshlrev_b32_e32 v38, 16, v7
	v_fma_f32 v44, -v41, v43, 1.0
	v_fmac_f32_e32 v43, v44, v43
	v_mul_f32_e32 v44, v42, v43
	v_fma_f32 v45, -v41, v44, v42
	v_fmac_f32_e32 v44, v45, v43
	v_fma_f32 v41, -v41, v44, v42
	v_div_fmas_f32 v41, v41, v43, v44
	v_div_fixup_f32 v0, v41, v0, 1.0
	v_and_b32_e32 v7, 0xffff0000, v7
	v_pk_mul_f32 v[18:19], v[18:19], v[0:1] op_sel_hi:[1,0]
	v_mul_f32_e32 v40, v40, v0
	v_pk_mul_f32 v[22:23], v[18:19], v[22:23] op_sel:[1,0] op_sel_hi:[0,1]
	v_pk_mul_f32 v[4:5], v[18:19], v[4:5] op_sel:[1,0] op_sel_hi:[0,1]
	v_pk_mul_f32 v[32:33], v[18:19], v[32:33] op_sel:[1,0] op_sel_hi:[0,1]
	v_pk_mul_f32 v[6:7], v[18:19], v[6:7] op_sel:[1,0] op_sel_hi:[0,1]
	v_pk_fma_f32 v[20:21], v[18:19], v[20:21], v[22:23]
	v_pk_fma_f32 v[4:5], v[18:19], v[30:31], v[4:5]
	v_pk_fma_f32 v[16:17], v[18:19], v[16:17], v[32:33]
	v_pk_fma_f32 v[6:7], v[18:19], v[38:39], v[6:7]
	v_pk_fma_f32 v[18:19], v[40:41], v[24:25], v[20:21] op_sel_hi:[0,1,1]
	v_pk_fma_f32 v[4:5], v[40:41], v[8:9], v[4:5] op_sel_hi:[0,1,1]
	v_pk_fma_f32 v[8:9], v[40:41], v[34:35], v[16:17] op_sel_hi:[0,1,1]
	v_pk_fma_f32 v[6:7], v[40:41], v[10:11], v[6:7] op_sel_hi:[0,1,1]
	v_pk_mul_f32 v[10:11], v[18:19], v[28:29]
	v_pk_mul_f32 v[12:13], v[4:5], v[12:13]
	v_pk_mul_f32 v[8:9], v[8:9], v[36:37]
	v_pk_mul_f32 v[14:15], v[6:7], v[14:15]
	v_cvt_pk_bf16_f32 v4, v10, v11
	v_cvt_pk_bf16_f32 v5, v12, v13
	v_cvt_pk_bf16_f32 v6, v8, v9
	v_cvt_pk_bf16_f32 v7, v14, v15
	global_store_dwordx4 v[26:27], v[4:7], off sc1
	s_nop 1
	s_waitcnt vmcnt(5)
	v_max3_f32 v90, v48, v88, v89
	v_sub_f32_e32 v48, v48, v90
	s_waitcnt vmcnt(4)
	v_lshlrev_b32_e32 v68, 16, v52
	s_waitcnt vmcnt(3)
	v_and_b32_e32 v69, 0xffff0000, v56
	s_waitcnt vmcnt(1)
	v_lshlrev_b32_e32 v84, 16, v66
	v_and_b32_e32 v85, 0xffff0000, v66
	v_sub_f32_e32 v66, v88, v90
	v_lshlrev_b32_e32 v70, 16, v56
	v_and_b32_e32 v71, 0xffff0000, v52
	v_lshlrev_b32_e32 v72, 16, v60
	v_and_b32_e32 v73, 0xffff0000, v60
	v_lshlrev_b32_e32 v76, 16, v64
	v_and_b32_e32 v77, 0xffff0000, v64
	v_and_b32_e32 v79, 0xffff0000, v57
	v_lshlrev_b32_e32 v52, 16, v57
	v_lshlrev_b32_e32 v56, 16, v61
	v_and_b32_e32 v57, 0xffff0000, v61
	v_lshlrev_b32_e32 v60, 16, v65
	v_and_b32_e32 v61, 0xffff0000, v65
	v_lshlrev_b32_e32 v64, 16, v54
	v_and_b32_e32 v65, 0xffff0000, v58
	v_lshlrev_b32_e32 v80, 16, v58
	v_and_b32_e32 v81, 0xffff0000, v54
	v_lshlrev_b32_e32 v82, 16, v62
	v_and_b32_e32 v83, 0xffff0000, v62
	v_and_b32_e32 v87, 0xffff0000, v59
	v_lshlrev_b32_e32 v54, 16, v59
	v_lshlrev_b32_e32 v58, 16, v63
	v_and_b32_e32 v59, 0xffff0000, v63
	v_lshlrev_b32_e32 v62, 16, v67
	v_and_b32_e32 v63, 0xffff0000, v67
	v_sub_f32_e32 v88, v89, v90
	v_exp_f32_e32 v67, v48
	v_exp_f32_e32 v66, v66
	v_exp_f32_e32 v88, v88
	v_lshlrev_b32_e32 v78, 16, v53
	v_and_b32_e32 v53, 0xffff0000, v53
	v_add_f32_e32 v48, v67, v66
	v_add_f32_e32 v48, v88, v48
	v_div_scale_f32 v89, s[20:21], v48, v48, 1.0
	v_rcp_f32_e32 v91, v89
	v_div_scale_f32 v90, vcc, 1.0, v48, 1.0
	v_lshlrev_b32_e32 v86, 16, v55
	v_fma_f32 v92, -v89, v91, 1.0
	v_fmac_f32_e32 v91, v92, v91
	v_mul_f32_e32 v92, v90, v91
	v_fma_f32 v93, -v89, v92, v90
	v_fmac_f32_e32 v92, v93, v91
	v_fma_f32 v89, -v89, v92, v90
	v_div_fmas_f32 v89, v89, v91, v92
	v_div_fixup_f32 v48, v89, v48, 1.0
	v_and_b32_e32 v55, 0xffff0000, v55
	v_pk_mul_f32 v[66:67], v[66:67], v[48:49] op_sel_hi:[1,0]
	v_mul_f32_e32 v88, v88, v48
	v_pk_mul_f32 v[70:71], v[66:67], v[70:71] op_sel:[1,0] op_sel_hi:[0,1]
	v_pk_mul_f32 v[52:53], v[66:67], v[52:53] op_sel:[1,0] op_sel_hi:[0,1]
	v_pk_mul_f32 v[80:81], v[66:67], v[80:81] op_sel:[1,0] op_sel_hi:[0,1]
	v_pk_mul_f32 v[54:55], v[66:67], v[54:55] op_sel:[1,0] op_sel_hi:[0,1]
	v_pk_fma_f32 v[68:69], v[66:67], v[68:69], v[70:71]
	v_pk_fma_f32 v[52:53], v[66:67], v[78:79], v[52:53]
	v_pk_fma_f32 v[64:65], v[66:67], v[64:65], v[80:81]
	v_pk_fma_f32 v[54:55], v[66:67], v[86:87], v[54:55]
	v_pk_fma_f32 v[66:67], v[88:89], v[72:73], v[68:69] op_sel_hi:[0,1,1]
	v_pk_fma_f32 v[52:53], v[88:89], v[56:57], v[52:53] op_sel_hi:[0,1,1]
	v_pk_fma_f32 v[56:57], v[88:89], v[82:83], v[64:65] op_sel_hi:[0,1,1]
	v_pk_fma_f32 v[54:55], v[88:89], v[58:59], v[54:55] op_sel_hi:[0,1,1]
	v_pk_mul_f32 v[58:59], v[66:67], v[76:77]
	v_pk_mul_f32 v[60:61], v[52:53], v[60:61]
	v_pk_mul_f32 v[56:57], v[56:57], v[84:85]
	v_pk_mul_f32 v[62:63], v[54:55], v[62:63]
	v_cvt_pk_bf16_f32 v52, v58, v59
	v_cvt_pk_bf16_f32 v53, v60, v61
	v_cvt_pk_bf16_f32 v54, v56, v57
	v_cvt_pk_bf16_f32 v55, v62, v63
	global_store_dwordx4 v[74:75], v[52:55], off sc1
	s_nop 1
	s_branch .Lmg_top
.Lmg_tail:
	s_add_i32 s24, s22, 0x18000
	s_cmp_gt_i32 s24, 0xfffff
	s_cbranch_scc1 .LBB0_450
